# mixer B: fast path owns its unit epilogue; its 8 gate loads are issued during the final tile-step
# baseline (speedup 1.0000x reference)
; __device__ __forceinline__ void attnB_unit(LAS unsigned char* lds, const Args& A, int unit, const float* kng, bool do_store = true) {
;     ...
;     if (fast) {
; #pragma unroll 1
;         for (int t = 0; t < NT; t += 2) { AB_STEP(c0, c1, d0, d1, t, kq1, vq1, kq0, vq0, true); AB_STEP(d0, d1, c0, c1, t + 1, kq0, vq0, kq1, vq1, true); }
.Lmixb_loop:
	v_mfma_f32_32x32x16_bf16 v[32:47], v[160:163], v[238:241], v[32:47]
	ds_read_b128 v[96:99], v172 offset:21504
	ds_read_b128 v[100:103], v172 offset:21536
	v_exp_f32_e32 v30, v30
	v_cvt_pk_bf16_f32 v244, v28, v29
	v_exp_f32_e32 v31, v31
	v_mfma_f32_32x32x16_bf16 v[48:63], v[164:167], v[238:241], v[48:63]
	v_mfma_f32_16x16x32_bf16 v[174:177], v[178:181], v[238:241], v[174:177]
	ds_read_b128 v[104:107], v172 offset:21568
	ds_read_b128 v[108:111], v172 offset:21600
	v_exp_f32_e32 v0, v0
	v_cvt_pk_bf16_f32 v245, v30, v31
	v_exp_f32_e32 v1, v1
	v_add_u32_e32 v214, 0x2000, v214
	global_load_dwordx4 v[152:155], v214, s[4:5]
	global_load_dwordx4 v[156:159], v214, s[6:7]
	v_mfma_f32_32x32x16_bf16 v[32:47], v[190:193], v[242:245], v[32:47]
	ds_read_b128 v[112:115], v172 offset:26112
	ds_read_b128 v[116:119], v172 offset:26144
	v_exp_f32_e32 v2, v2
	v_cvt_pk_bf16_f32 v246, v0, v1
	v_exp_f32_e32 v3, v3
	v_mfma_f32_32x32x16_bf16 v[48:63], v[194:197], v[242:245], v[48:63]
	v_mfma_f32_16x16x32_bf16 v[174:177], v[178:181], v[242:245], v[174:177]
	ds_read_b128 v[120:123], v172 offset:26176
	ds_read_b128 v[124:127], v172 offset:26208
	v_exp_f32_e32 v4, v4
	v_cvt_pk_bf16_f32 v247, v2, v3
	v_exp_f32_e32 v5, v5
	s_waitcnt lgkmcnt(4)
	v_mfma_f32_32x32x16_bf16 v[80:95], v[96:99], v[128:131], 0
	v_exp_f32_e32 v6, v6
	v_cvt_pk_bf16_f32 v248, v4, v5
	v_exp_f32_e32 v7, v7
	ds_read_b64_tr_b16 v[198:199], v182 offset:15360
	ds_read_b64_tr_b16 v[200:201], v182 offset:16896
	v_mfma_f32_32x32x16_bf16 v[80:95], v[100:103], v[132:135], v[80:95]
	v_exp_f32_e32 v8, v8
	v_cvt_pk_bf16_f32 v249, v6, v7
	v_exp_f32_e32 v9, v9
	ds_read_b64_tr_b16 v[202:203], v182 offset:15424
	ds_read_b64_tr_b16 v[204:205], v182 offset:16960
	v_mfma_f32_32x32x16_bf16 v[80:95], v[104:107], v[136:139], v[80:95]
	v_exp_f32_e32 v10, v10
	v_cvt_pk_bf16_f32 v250, v8, v9
	v_exp_f32_e32 v11, v11
	ds_read_b64_tr_b16 v[206:207], v182 offset:18432
	ds_read_b64_tr_b16 v[208:209], v182 offset:19968
	v_mfma_f32_32x32x16_bf16 v[80:95], v[108:111], v[140:143], v[80:95]
	v_exp_f32_e32 v12, v12
	v_cvt_pk_bf16_f32 v251, v10, v11
	v_exp_f32_e32 v13, v13
	ds_read_b64_tr_b16 v[234:235], v182 offset:18496
	ds_read_b64_tr_b16 v[236:237], v182 offset:20032
	s_waitcnt lgkmcnt(8)
	v_mfma_f32_32x32x16_bf16 v[64:79], v[112:115], v[128:131], 0
	v_exp_f32_e32 v14, v14
	v_cvt_pk_bf16_f32 v252, v12, v13
	v_exp_f32_e32 v15, v15
	ds_read_b64_tr_b16 v[160:161], v182 offset:30720
	ds_read_b64_tr_b16 v[162:163], v182 offset:32256
	v_mfma_f32_32x32x16_bf16 v[64:79], v[116:119], v[132:135], v[64:79]
	v_exp_f32_e32 v80, v80
	v_cvt_pk_bf16_f32 v253, v14, v15
	v_exp_f32_e32 v81, v81
	ds_read_b64_tr_b16 v[164:165], v182 offset:30784
	ds_read_b64_tr_b16 v[166:167], v182 offset:32320
	v_mfma_f32_32x32x16_bf16 v[64:79], v[120:123], v[136:139], v[64:79]
	v_exp_f32_e32 v82, v82
	v_cvt_pk_bf16_f32 v238, v80, v81
	v_exp_f32_e32 v83, v83
	ds_read_b64_tr_b16 v[190:191], v182 offset:33792
	ds_read_b64_tr_b16 v[192:193], v182 offset:35328
	v_mfma_f32_32x32x16_bf16 v[64:79], v[124:127], v[140:143], v[64:79]
	v_exp_f32_e32 v84, v84
	v_cvt_pk_bf16_f32 v239, v82, v83
	v_exp_f32_e32 v85, v85
	ds_read_b64_tr_b16 v[194:195], v182 offset:33856
	ds_read_b64_tr_b16 v[196:197], v182 offset:35392
	s_waitcnt lgkmcnt(8)
	v_mfma_f32_32x32x16_bf16 v[32:47], v[198:201], v[246:249], v[32:47]
	v_exp_f32_e32 v86, v86
	v_cvt_pk_bf16_f32 v240, v84, v85
	v_exp_f32_e32 v87, v87
	s_waitcnt vmcnt(2)
	ds_write_b128 v187, v[144:147]
	v_mfma_f32_32x32x16_bf16 v[48:63], v[202:205], v[246:249], v[48:63]
	v_mfma_f32_16x16x32_bf16 v[174:177], v[178:181], v[246:249], v[174:177]
	v_exp_f32_e32 v88, v88
	v_cvt_pk_bf16_f32 v241, v86, v87
	v_exp_f32_e32 v89, v89
	ds_write_b128 v189, v[148:151] offset:9216
	v_mfma_f32_32x32x16_bf16 v[32:47], v[206:209], v[250:253], v[32:47]
	v_exp_f32_e32 v90, v90
	v_cvt_pk_bf16_f32 v242, v88, v89
	v_exp_f32_e32 v91, v91
	v_mfma_f32_32x32x16_bf16 v[48:63], v[234:237], v[250:253], v[48:63]
	v_mfma_f32_16x16x32_bf16 v[174:177], v[178:181], v[250:253], v[174:177]
	v_exp_f32_e32 v92, v92
	v_cvt_pk_bf16_f32 v243, v90, v91
	v_exp_f32_e32 v93, v93
	s_waitcnt lgkmcnt(0)
	s_barrier
	v_mfma_f32_32x32x16_bf16 v[32:47], v[160:163], v[238:241], v[32:47]
	ds_read_b128 v[96:99], v173
	ds_read_b128 v[100:103], v173 offset:32
	v_exp_f32_e32 v94, v94
	v_cvt_pk_bf16_f32 v244, v92, v93
	v_exp_f32_e32 v95, v95
	v_mfma_f32_32x32x16_bf16 v[48:63], v[164:167], v[238:241], v[48:63]
	v_mfma_f32_16x16x32_bf16 v[174:177], v[178:181], v[238:241], v[174:177]
	ds_read_b128 v[104:107], v173 offset:64
	ds_read_b128 v[108:111], v173 offset:96
	v_exp_f32_e32 v64, v64
	v_cvt_pk_bf16_f32 v245, v94, v95
	v_exp_f32_e32 v65, v65
	v_add_u32_e32 v214, 0x2000, v214
	global_load_dwordx4 v[144:147], v214, s[4:5]
	global_load_dwordx4 v[148:151], v214, s[6:7]
	v_mfma_f32_32x32x16_bf16 v[32:47], v[190:193], v[242:245], v[32:47]
	ds_read_b128 v[112:115], v173 offset:4608
	ds_read_b128 v[116:119], v173 offset:4640
	v_exp_f32_e32 v66, v66
	v_cvt_pk_bf16_f32 v246, v64, v65
	v_exp_f32_e32 v67, v67
	v_mfma_f32_32x32x16_bf16 v[48:63], v[194:197], v[242:245], v[48:63]
	v_mfma_f32_16x16x32_bf16 v[174:177], v[178:181], v[242:245], v[174:177]
	ds_read_b128 v[120:123], v173 offset:4672
	ds_read_b128 v[124:127], v173 offset:4704
	v_exp_f32_e32 v68, v68
	v_cvt_pk_bf16_f32 v247, v66, v67
	v_exp_f32_e32 v69, v69
	s_waitcnt lgkmcnt(4)
	v_mfma_f32_32x32x16_bf16 v[16:31], v[96:99], v[128:131], 0
	v_exp_f32_e32 v70, v70
	v_cvt_pk_bf16_f32 v248, v68, v69
	v_exp_f32_e32 v71, v71
	ds_read_b64_tr_b16 v[198:199], v182 offset:36864
	ds_read_b64_tr_b16 v[200:201], v182 offset:38400
	v_mfma_f32_32x32x16_bf16 v[16:31], v[100:103], v[132:135], v[16:31]
	v_exp_f32_e32 v72, v72
	v_cvt_pk_bf16_f32 v249, v70, v71
	v_exp_f32_e32 v73, v73
	ds_read_b64_tr_b16 v[202:203], v182 offset:36928
	ds_read_b64_tr_b16 v[204:205], v182 offset:38464
	v_mfma_f32_32x32x16_bf16 v[16:31], v[104:107], v[136:139], v[16:31]
	v_exp_f32_e32 v74, v74
	v_cvt_pk_bf16_f32 v250, v72, v73
	v_exp_f32_e32 v75, v75
	ds_read_b64_tr_b16 v[206:207], v182 offset:39936
	ds_read_b64_tr_b16 v[208:209], v182 offset:41472
	v_mfma_f32_32x32x16_bf16 v[16:31], v[108:111], v[140:143], v[16:31]
	v_exp_f32_e32 v76, v76
	v_cvt_pk_bf16_f32 v251, v74, v75
	v_exp_f32_e32 v77, v77
	ds_read_b64_tr_b16 v[234:235], v182 offset:40000
	ds_read_b64_tr_b16 v[236:237], v182 offset:41536
	s_waitcnt lgkmcnt(8)
	v_mfma_f32_32x32x16_bf16 v[0:15], v[112:115], v[128:131], 0
	v_exp_f32_e32 v78, v78
	v_cvt_pk_bf16_f32 v252, v76, v77
	v_exp_f32_e32 v79, v79
	ds_read_b64_tr_b16 v[160:161], v183 offset:9216
	ds_read_b64_tr_b16 v[162:163], v183 offset:10752
	v_mfma_f32_32x32x16_bf16 v[0:15], v[116:119], v[132:135], v[0:15]
	v_exp_f32_e32 v16, v16
	v_cvt_pk_bf16_f32 v253, v78, v79
	v_exp_f32_e32 v17, v17
	ds_read_b64_tr_b16 v[164:165], v183 offset:9280
	ds_read_b64_tr_b16 v[166:167], v183 offset:10816
	v_mfma_f32_32x32x16_bf16 v[0:15], v[120:123], v[136:139], v[0:15]
	v_exp_f32_e32 v18, v18
	v_cvt_pk_bf16_f32 v238, v16, v17
	v_exp_f32_e32 v19, v19
	ds_read_b64_tr_b16 v[190:191], v183 offset:12288
	ds_read_b64_tr_b16 v[192:193], v183 offset:13824
	v_mfma_f32_32x32x16_bf16 v[0:15], v[124:127], v[140:143], v[0:15]
	v_exp_f32_e32 v20, v20
	v_cvt_pk_bf16_f32 v239, v18, v19
	v_exp_f32_e32 v21, v21
	ds_read_b64_tr_b16 v[194:195], v183 offset:12352
	ds_read_b64_tr_b16 v[196:197], v183 offset:13888
	s_waitcnt lgkmcnt(8)
	v_mfma_f32_32x32x16_bf16 v[32:47], v[198:201], v[246:249], v[32:47]
	v_exp_f32_e32 v22, v22
	v_cvt_pk_bf16_f32 v240, v20, v21
	v_exp_f32_e32 v23, v23
	s_waitcnt vmcnt(2)
	ds_write_b128 v187, v[152:155] offset:21504
	v_mfma_f32_32x32x16_bf16 v[48:63], v[202:205], v[246:249], v[48:63]
	v_mfma_f32_16x16x32_bf16 v[174:177], v[178:181], v[246:249], v[174:177]
	v_exp_f32_e32 v24, v24
	v_cvt_pk_bf16_f32 v241, v22, v23
	v_exp_f32_e32 v25, v25
	ds_write_b128 v189, v[156:159] offset:30720
	v_mfma_f32_32x32x16_bf16 v[32:47], v[206:209], v[250:253], v[32:47]
	v_exp_f32_e32 v26, v26
	v_cvt_pk_bf16_f32 v242, v24, v25
	v_exp_f32_e32 v27, v27
	v_mfma_f32_32x32x16_bf16 v[48:63], v[234:237], v[250:253], v[48:63]
	v_mfma_f32_16x16x32_bf16 v[174:177], v[178:181], v[250:253], v[174:177]
	v_exp_f32_e32 v28, v28
	v_cvt_pk_bf16_f32 v243, v26, v27
	v_exp_f32_e32 v29, v29
	s_waitcnt lgkmcnt(0)
	s_barrier
	v_mfma_f32_32x32x16_bf16 v[32:47], v[160:163], v[238:241], v[32:47]
	ds_read_b128 v[96:99], v173 offset:21504
	ds_read_b128 v[100:103], v173 offset:21536
	v_exp_f32_e32 v30, v30
	v_cvt_pk_bf16_f32 v244, v28, v29
	v_exp_f32_e32 v31, v31
	v_mfma_f32_32x32x16_bf16 v[48:63], v[164:167], v[238:241], v[48:63]
	v_mfma_f32_16x16x32_bf16 v[174:177], v[178:181], v[238:241], v[174:177]
	ds_read_b128 v[104:107], v173 offset:21568
	ds_read_b128 v[108:111], v173 offset:21600
	v_exp_f32_e32 v0, v0
	v_cvt_pk_bf16_f32 v245, v30, v31
	v_exp_f32_e32 v1, v1
	v_add_u32_e32 v214, 0x2000, v214
	global_load_dwordx4 v[152:155], v214, s[4:5]
	global_load_dwordx4 v[156:159], v214, s[6:7]
	v_mfma_f32_32x32x16_bf16 v[32:47], v[190:193], v[242:245], v[32:47]
	ds_read_b128 v[112:115], v173 offset:26112
	ds_read_b128 v[116:119], v173 offset:26144
	v_exp_f32_e32 v2, v2
	v_cvt_pk_bf16_f32 v246, v0, v1
	v_exp_f32_e32 v3, v3
	v_mfma_f32_32x32x16_bf16 v[48:63], v[194:197], v[242:245], v[48:63]
	v_mfma_f32_16x16x32_bf16 v[174:177], v[178:181], v[242:245], v[174:177]
	ds_read_b128 v[120:123], v173 offset:26176
	ds_read_b128 v[124:127], v173 offset:26208
	v_exp_f32_e32 v4, v4
	v_cvt_pk_bf16_f32 v247, v2, v3
	v_exp_f32_e32 v5, v5
	s_waitcnt lgkmcnt(4)
	v_mfma_f32_32x32x16_bf16 v[80:95], v[96:99], v[128:131], 0
	v_exp_f32_e32 v6, v6
	v_cvt_pk_bf16_f32 v248, v4, v5
	v_exp_f32_e32 v7, v7
	ds_read_b64_tr_b16 v[198:199], v183 offset:15360
	ds_read_b64_tr_b16 v[200:201], v183 offset:16896
	v_mfma_f32_32x32x16_bf16 v[80:95], v[100:103], v[132:135], v[80:95]
	v_exp_f32_e32 v8, v8
	v_cvt_pk_bf16_f32 v249, v6, v7
	v_exp_f32_e32 v9, v9
	ds_read_b64_tr_b16 v[202:203], v183 offset:15424
	ds_read_b64_tr_b16 v[204:205], v183 offset:16960
	v_mfma_f32_32x32x16_bf16 v[80:95], v[104:107], v[136:139], v[80:95]
	v_exp_f32_e32 v10, v10
	v_cvt_pk_bf16_f32 v250, v8, v9
	v_exp_f32_e32 v11, v11
	ds_read_b64_tr_b16 v[206:207], v183 offset:18432
	ds_read_b64_tr_b16 v[208:209], v183 offset:19968
	v_mfma_f32_32x32x16_bf16 v[80:95], v[108:111], v[140:143], v[80:95]
	v_exp_f32_e32 v12, v12
	v_cvt_pk_bf16_f32 v251, v10, v11
	v_exp_f32_e32 v13, v13
	ds_read_b64_tr_b16 v[234:235], v183 offset:18496
	ds_read_b64_tr_b16 v[236:237], v183 offset:20032
	s_waitcnt lgkmcnt(8)
; __device__ __forceinline__ void attnB_unit(LAS unsigned char* lds, const Args& A, int unit, const float* kng, bool do_store = true) {
;     ...
;     if (fast) {
; #pragma unroll 1
;         for (int t = 0; t < NT; t += 2) { AB_STEP(c0, c1, d0, d1, t, kq1, vq1, kq0, vq0, true); AB_STEP(d0, d1, c0, c1, t + 1, kq0, vq0, kq1, vq1, true); }
	v_mfma_f32_32x32x16_bf16 v[64:79], v[112:115], v[128:131], 0
	v_exp_f32_e32 v14, v14
	v_cvt_pk_bf16_f32 v252, v12, v13
	v_exp_f32_e32 v15, v15
	ds_read_b64_tr_b16 v[160:161], v183 offset:30720
	ds_read_b64_tr_b16 v[162:163], v183 offset:32256
	v_mfma_f32_32x32x16_bf16 v[64:79], v[116:119], v[132:135], v[64:79]
	v_exp_f32_e32 v80, v80
	v_cvt_pk_bf16_f32 v253, v14, v15
	v_exp_f32_e32 v81, v81
	ds_read_b64_tr_b16 v[164:165], v183 offset:30784
	ds_read_b64_tr_b16 v[166:167], v183 offset:32320
	v_mfma_f32_32x32x16_bf16 v[64:79], v[120:123], v[136:139], v[64:79]
	v_exp_f32_e32 v82, v82
	v_cvt_pk_bf16_f32 v238, v80, v81
	v_exp_f32_e32 v83, v83
	ds_read_b64_tr_b16 v[190:191], v183 offset:33792
	ds_read_b64_tr_b16 v[192:193], v183 offset:35328
	v_mfma_f32_32x32x16_bf16 v[64:79], v[124:127], v[140:143], v[64:79]
	v_exp_f32_e32 v84, v84
	v_cvt_pk_bf16_f32 v239, v82, v83
	v_exp_f32_e32 v85, v85
	ds_read_b64_tr_b16 v[194:195], v183 offset:33856
	ds_read_b64_tr_b16 v[196:197], v183 offset:35392
	s_waitcnt lgkmcnt(8)
	v_mfma_f32_32x32x16_bf16 v[32:47], v[198:201], v[246:249], v[32:47]
	v_exp_f32_e32 v86, v86
	v_cvt_pk_bf16_f32 v240, v84, v85
	v_exp_f32_e32 v87, v87
	s_waitcnt vmcnt(2)
	ds_write_b128 v186, v[144:147]
	v_mfma_f32_32x32x16_bf16 v[48:63], v[202:205], v[246:249], v[48:63]
	v_mfma_f32_16x16x32_bf16 v[174:177], v[178:181], v[246:249], v[174:177]
	v_exp_f32_e32 v88, v88
	v_cvt_pk_bf16_f32 v241, v86, v87
	v_exp_f32_e32 v89, v89
	ds_write_b128 v188, v[148:151] offset:9216
	v_mfma_f32_32x32x16_bf16 v[32:47], v[206:209], v[250:253], v[32:47]
	v_exp_f32_e32 v90, v90
	v_cvt_pk_bf16_f32 v242, v88, v89
	v_exp_f32_e32 v91, v91
	v_mfma_f32_32x32x16_bf16 v[48:63], v[234:237], v[250:253], v[48:63]
	v_mfma_f32_16x16x32_bf16 v[174:177], v[178:181], v[250:253], v[174:177]
	v_exp_f32_e32 v92, v92
	v_cvt_pk_bf16_f32 v243, v90, v91
	v_exp_f32_e32 v93, v93
	s_waitcnt lgkmcnt(0)
	s_barrier
	v_mfma_f32_32x32x16_bf16 v[32:47], v[160:163], v[238:241], v[32:47]
	ds_read_b128 v[96:99], v172
	ds_read_b128 v[100:103], v172 offset:32
	v_exp_f32_e32 v94, v94
	v_cvt_pk_bf16_f32 v244, v92, v93
	v_exp_f32_e32 v95, v95
	v_mfma_f32_32x32x16_bf16 v[48:63], v[164:167], v[238:241], v[48:63]
	v_mfma_f32_16x16x32_bf16 v[174:177], v[178:181], v[238:241], v[174:177]
	ds_read_b128 v[104:107], v172 offset:64
	ds_read_b128 v[108:111], v172 offset:96
	v_exp_f32_e32 v64, v64
	v_cvt_pk_bf16_f32 v245, v94, v95
	v_exp_f32_e32 v65, v65
	v_add_u32_e32 v214, 0x2000, v214
	global_load_dwordx4 v[144:147], v214, s[4:5]
	global_load_dwordx4 v[148:151], v214, s[6:7]
	v_mfma_f32_32x32x16_bf16 v[32:47], v[190:193], v[242:245], v[32:47]
	ds_read_b128 v[112:115], v172 offset:4608
	ds_read_b128 v[116:119], v172 offset:4640
	v_exp_f32_e32 v66, v66
	v_cvt_pk_bf16_f32 v246, v64, v65
	v_exp_f32_e32 v67, v67
	v_mfma_f32_32x32x16_bf16 v[48:63], v[194:197], v[242:245], v[48:63]
	v_mfma_f32_16x16x32_bf16 v[174:177], v[178:181], v[242:245], v[174:177]
	ds_read_b128 v[120:123], v172 offset:4672
	ds_read_b128 v[124:127], v172 offset:4704
	v_exp_f32_e32 v68, v68
	v_cvt_pk_bf16_f32 v247, v66, v67
	v_exp_f32_e32 v69, v69
	s_waitcnt lgkmcnt(4)
	v_mfma_f32_32x32x16_bf16 v[16:31], v[96:99], v[128:131], 0
	v_exp_f32_e32 v70, v70
	v_cvt_pk_bf16_f32 v248, v68, v69
	v_exp_f32_e32 v71, v71
	ds_read_b64_tr_b16 v[198:199], v183 offset:36864
	ds_read_b64_tr_b16 v[200:201], v183 offset:38400
	v_mfma_f32_32x32x16_bf16 v[16:31], v[100:103], v[132:135], v[16:31]
	v_exp_f32_e32 v72, v72
	v_cvt_pk_bf16_f32 v249, v70, v71
	v_exp_f32_e32 v73, v73
	ds_read_b64_tr_b16 v[202:203], v183 offset:36928
	ds_read_b64_tr_b16 v[204:205], v183 offset:38464
	v_mfma_f32_32x32x16_bf16 v[16:31], v[104:107], v[136:139], v[16:31]
	v_exp_f32_e32 v74, v74
	v_cvt_pk_bf16_f32 v250, v72, v73
	v_exp_f32_e32 v75, v75
	ds_read_b64_tr_b16 v[206:207], v183 offset:39936
	ds_read_b64_tr_b16 v[208:209], v183 offset:41472
	v_mfma_f32_32x32x16_bf16 v[16:31], v[108:111], v[140:143], v[16:31]
	v_exp_f32_e32 v76, v76
	v_cvt_pk_bf16_f32 v251, v74, v75
	v_exp_f32_e32 v77, v77
	ds_read_b64_tr_b16 v[234:235], v183 offset:40000
	ds_read_b64_tr_b16 v[236:237], v183 offset:41536
	s_waitcnt lgkmcnt(8)
	v_mfma_f32_32x32x16_bf16 v[0:15], v[112:115], v[128:131], 0
	v_exp_f32_e32 v78, v78
	v_cvt_pk_bf16_f32 v252, v76, v77
	v_exp_f32_e32 v79, v79
	ds_read_b64_tr_b16 v[160:161], v182 offset:9216
	ds_read_b64_tr_b16 v[162:163], v182 offset:10752
	v_mfma_f32_32x32x16_bf16 v[0:15], v[116:119], v[132:135], v[0:15]
	v_exp_f32_e32 v16, v16
	v_cvt_pk_bf16_f32 v253, v78, v79
	v_exp_f32_e32 v17, v17
	ds_read_b64_tr_b16 v[164:165], v182 offset:9280
	ds_read_b64_tr_b16 v[166:167], v182 offset:10816
	v_mfma_f32_32x32x16_bf16 v[0:15], v[120:123], v[136:139], v[0:15]
	v_exp_f32_e32 v18, v18
	v_cvt_pk_bf16_f32 v238, v16, v17
	v_exp_f32_e32 v19, v19
	ds_read_b64_tr_b16 v[190:191], v182 offset:12288
	ds_read_b64_tr_b16 v[192:193], v182 offset:13824
	v_mfma_f32_32x32x16_bf16 v[0:15], v[124:127], v[140:143], v[0:15]
	v_exp_f32_e32 v20, v20
	v_cvt_pk_bf16_f32 v239, v18, v19
	v_exp_f32_e32 v21, v21
	ds_read_b64_tr_b16 v[194:195], v182 offset:12352
	ds_read_b64_tr_b16 v[196:197], v182 offset:13888
	s_waitcnt lgkmcnt(8)
	v_mfma_f32_32x32x16_bf16 v[32:47], v[198:201], v[246:249], v[32:47]
	v_exp_f32_e32 v22, v22
	v_cvt_pk_bf16_f32 v240, v20, v21
	v_exp_f32_e32 v23, v23
	s_waitcnt vmcnt(2)
	ds_write_b128 v186, v[152:155] offset:21504
	v_mfma_f32_32x32x16_bf16 v[48:63], v[202:205], v[246:249], v[48:63]
	v_mfma_f32_16x16x32_bf16 v[174:177], v[178:181], v[246:249], v[174:177]
	v_exp_f32_e32 v24, v24
	v_cvt_pk_bf16_f32 v241, v22, v23
	v_exp_f32_e32 v25, v25
	ds_write_b128 v188, v[156:159] offset:30720
	v_mfma_f32_32x32x16_bf16 v[32:47], v[206:209], v[250:253], v[32:47]
	v_exp_f32_e32 v26, v26
	v_cvt_pk_bf16_f32 v242, v24, v25
	v_exp_f32_e32 v27, v27
	v_mfma_f32_32x32x16_bf16 v[48:63], v[234:237], v[250:253], v[48:63]
	v_mfma_f32_16x16x32_bf16 v[174:177], v[178:181], v[250:253], v[174:177]
	v_exp_f32_e32 v28, v28
	v_cvt_pk_bf16_f32 v243, v26, v27
	v_exp_f32_e32 v29, v29
	s_add_i32 s11, s11, -1
	s_cmp_lg_u32 s11, 0
	s_waitcnt lgkmcnt(0)
	s_barrier
; __device__ __forceinline__ void attnB_unit(LAS unsigned char* lds, const Args& A, int unit, const float* kng, bool do_store = true) {
;     ...
;     if (fast) {
; #pragma unroll 1
;         for (int t = 0; t < NT; t += 2) { AB_STEP(c0, c1, d0, d1, t, kq1, vq1, kq0, vq0, true); AB_STEP(d0, d1, c0, c1, t + 1, kq0, vq0, kq1, vq1, true); }
	s_cbranch_scc1 .Lmixb_loop
	v_mfma_f32_32x32x16_bf16 v[32:47], v[160:163], v[238:241], v[32:47]
	ds_read_b128 v[96:99], v172 offset:21504
	ds_read_b128 v[100:103], v172 offset:21536
	v_exp_f32_e32 v30, v30
	v_cvt_pk_bf16_f32 v244, v28, v29
	v_exp_f32_e32 v31, v31
	v_mfma_f32_32x32x16_bf16 v[48:63], v[164:167], v[238:241], v[48:63]
	v_mfma_f32_16x16x32_bf16 v[174:177], v[178:181], v[238:241], v[174:177]
	ds_read_b128 v[104:107], v172 offset:21568
	ds_read_b128 v[108:111], v172 offset:21600
	v_exp_f32_e32 v0, v0
	v_cvt_pk_bf16_f32 v245, v30, v31
	v_exp_f32_e32 v1, v1
	v_add_u32_e32 v214, 0x2000, v214
	global_load_dwordx4 v[152:155], v214, s[4:5]
	global_load_dwordx4 v[156:159], v214, s[6:7]
	v_mfma_f32_32x32x16_bf16 v[32:47], v[190:193], v[242:245], v[32:47]
	ds_read_b128 v[112:115], v172 offset:26112
	ds_read_b128 v[116:119], v172 offset:26144
	v_exp_f32_e32 v2, v2
	v_cvt_pk_bf16_f32 v246, v0, v1
	v_exp_f32_e32 v3, v3
	v_mfma_f32_32x32x16_bf16 v[48:63], v[194:197], v[242:245], v[48:63]
	v_mfma_f32_16x16x32_bf16 v[174:177], v[178:181], v[242:245], v[174:177]
	ds_read_b128 v[120:123], v172 offset:26176
	ds_read_b128 v[124:127], v172 offset:26208
	v_exp_f32_e32 v4, v4
	v_cvt_pk_bf16_f32 v247, v2, v3
	v_exp_f32_e32 v5, v5
	s_waitcnt lgkmcnt(4)
	v_mfma_f32_32x32x16_bf16 v[80:95], v[96:99], v[128:131], 0
	v_exp_f32_e32 v6, v6
	v_cvt_pk_bf16_f32 v248, v4, v5
	v_exp_f32_e32 v7, v7
	ds_read_b64_tr_b16 v[198:199], v182 offset:15360
	ds_read_b64_tr_b16 v[200:201], v182 offset:16896
	v_mfma_f32_32x32x16_bf16 v[80:95], v[100:103], v[132:135], v[80:95]
	v_exp_f32_e32 v8, v8
	v_cvt_pk_bf16_f32 v249, v6, v7
	v_exp_f32_e32 v9, v9
	ds_read_b64_tr_b16 v[202:203], v182 offset:15424
	ds_read_b64_tr_b16 v[204:205], v182 offset:16960
	v_mfma_f32_32x32x16_bf16 v[80:95], v[104:107], v[136:139], v[80:95]
	v_exp_f32_e32 v10, v10
	v_cvt_pk_bf16_f32 v250, v8, v9
	v_exp_f32_e32 v11, v11
	ds_read_b64_tr_b16 v[206:207], v182 offset:18432
	ds_read_b64_tr_b16 v[208:209], v182 offset:19968
	v_mfma_f32_32x32x16_bf16 v[80:95], v[108:111], v[140:143], v[80:95]
	v_exp_f32_e32 v12, v12
	v_cvt_pk_bf16_f32 v251, v10, v11
	v_exp_f32_e32 v13, v13
	ds_read_b64_tr_b16 v[234:235], v182 offset:18496
	ds_read_b64_tr_b16 v[236:237], v182 offset:20032
	s_waitcnt lgkmcnt(8)
	v_mfma_f32_32x32x16_bf16 v[64:79], v[112:115], v[128:131], 0
	v_exp_f32_e32 v14, v14
	v_cvt_pk_bf16_f32 v252, v12, v13
	v_exp_f32_e32 v15, v15
	ds_read_b64_tr_b16 v[160:161], v182 offset:30720
	ds_read_b64_tr_b16 v[162:163], v182 offset:32256
	v_mfma_f32_32x32x16_bf16 v[64:79], v[116:119], v[132:135], v[64:79]
	v_exp_f32_e32 v80, v80
	v_cvt_pk_bf16_f32 v253, v14, v15
	v_exp_f32_e32 v81, v81
	ds_read_b64_tr_b16 v[164:165], v182 offset:30784
	ds_read_b64_tr_b16 v[166:167], v182 offset:32320
	v_mfma_f32_32x32x16_bf16 v[64:79], v[120:123], v[136:139], v[64:79]
	v_exp_f32_e32 v82, v82
	v_cvt_pk_bf16_f32 v238, v80, v81
	v_exp_f32_e32 v83, v83
	ds_read_b64_tr_b16 v[190:191], v182 offset:33792
	ds_read_b64_tr_b16 v[192:193], v182 offset:35328
	v_mfma_f32_32x32x16_bf16 v[64:79], v[124:127], v[140:143], v[64:79]
	v_exp_f32_e32 v84, v84
	v_cvt_pk_bf16_f32 v239, v82, v83
	v_exp_f32_e32 v85, v85
	ds_read_b64_tr_b16 v[194:195], v182 offset:33856
	ds_read_b64_tr_b16 v[196:197], v182 offset:35392
	s_waitcnt lgkmcnt(8)
	v_mfma_f32_32x32x16_bf16 v[32:47], v[198:201], v[246:249], v[32:47]
	v_exp_f32_e32 v86, v86
	v_cvt_pk_bf16_f32 v240, v84, v85
	v_exp_f32_e32 v87, v87
	s_waitcnt vmcnt(2)
	ds_write_b128 v187, v[144:147]
	v_mfma_f32_32x32x16_bf16 v[48:63], v[202:205], v[246:249], v[48:63]
	v_mfma_f32_16x16x32_bf16 v[174:177], v[178:181], v[246:249], v[174:177]
	v_exp_f32_e32 v88, v88
	v_cvt_pk_bf16_f32 v241, v86, v87
	v_exp_f32_e32 v89, v89
	ds_write_b128 v189, v[148:151] offset:9216
	v_mfma_f32_32x32x16_bf16 v[32:47], v[206:209], v[250:253], v[32:47]
	v_exp_f32_e32 v90, v90
	v_cvt_pk_bf16_f32 v242, v88, v89
	v_exp_f32_e32 v91, v91
	v_mfma_f32_32x32x16_bf16 v[48:63], v[234:237], v[250:253], v[48:63]
	v_mfma_f32_16x16x32_bf16 v[174:177], v[178:181], v[250:253], v[174:177]
	v_exp_f32_e32 v92, v92
	v_cvt_pk_bf16_f32 v243, v90, v91
	v_exp_f32_e32 v93, v93
	s_waitcnt lgkmcnt(0)
	s_barrier
	v_mfma_f32_32x32x16_bf16 v[32:47], v[160:163], v[238:241], v[32:47]
	ds_read_b128 v[96:99], v173
	ds_read_b128 v[100:103], v173 offset:32
	v_exp_f32_e32 v94, v94
	v_cvt_pk_bf16_f32 v244, v92, v93
	v_exp_f32_e32 v95, v95
	v_mfma_f32_32x32x16_bf16 v[48:63], v[164:167], v[238:241], v[48:63]
	v_mfma_f32_16x16x32_bf16 v[174:177], v[178:181], v[238:241], v[174:177]
	ds_read_b128 v[104:107], v173 offset:64
	ds_read_b128 v[108:111], v173 offset:96
	v_exp_f32_e32 v64, v64
	v_cvt_pk_bf16_f32 v245, v94, v95
	v_exp_f32_e32 v65, v65
	s_nop 0
	v_mfma_f32_32x32x16_bf16 v[32:47], v[190:193], v[242:245], v[32:47]
	ds_read_b128 v[112:115], v173 offset:4608
	ds_read_b128 v[116:119], v173 offset:4640
	v_exp_f32_e32 v66, v66
	v_cvt_pk_bf16_f32 v246, v64, v65
	v_exp_f32_e32 v67, v67
	v_mfma_f32_32x32x16_bf16 v[48:63], v[194:197], v[242:245], v[48:63]
	v_mfma_f32_16x16x32_bf16 v[174:177], v[178:181], v[242:245], v[174:177]
	ds_read_b128 v[120:123], v173 offset:4672
	ds_read_b128 v[124:127], v173 offset:4704
	v_exp_f32_e32 v68, v68
	v_cvt_pk_bf16_f32 v247, v66, v67
	v_exp_f32_e32 v69, v69
	s_waitcnt lgkmcnt(4)
	v_mfma_f32_32x32x16_bf16 v[16:31], v[96:99], v[128:131], 0
	v_exp_f32_e32 v70, v70
	v_cvt_pk_bf16_f32 v248, v68, v69
	v_exp_f32_e32 v71, v71
	ds_read_b64_tr_b16 v[198:199], v182 offset:36864
	ds_read_b64_tr_b16 v[200:201], v182 offset:38400
	v_mfma_f32_32x32x16_bf16 v[16:31], v[100:103], v[132:135], v[16:31]
	v_exp_f32_e32 v72, v72
	v_cvt_pk_bf16_f32 v249, v70, v71
	v_exp_f32_e32 v73, v73
	ds_read_b64_tr_b16 v[202:203], v182 offset:36928
	ds_read_b64_tr_b16 v[204:205], v182 offset:38464
	v_mfma_f32_32x32x16_bf16 v[16:31], v[104:107], v[136:139], v[16:31]
	v_exp_f32_e32 v74, v74
	v_cvt_pk_bf16_f32 v250, v72, v73
	v_exp_f32_e32 v75, v75
	ds_read_b64_tr_b16 v[206:207], v182 offset:39936
	ds_read_b64_tr_b16 v[208:209], v182 offset:41472
	v_mfma_f32_32x32x16_bf16 v[16:31], v[108:111], v[140:143], v[16:31]
	v_exp_f32_e32 v76, v76
	v_cvt_pk_bf16_f32 v251, v74, v75
	v_exp_f32_e32 v77, v77
	ds_read_b64_tr_b16 v[234:235], v182 offset:40000
	ds_read_b64_tr_b16 v[236:237], v182 offset:41536
	s_waitcnt lgkmcnt(8)
	v_mfma_f32_32x32x16_bf16 v[0:15], v[112:115], v[128:131], 0
	v_exp_f32_e32 v78, v78
	v_cvt_pk_bf16_f32 v252, v76, v77
	v_exp_f32_e32 v79, v79
	ds_read_b64_tr_b16 v[160:161], v183 offset:9216
	ds_read_b64_tr_b16 v[162:163], v183 offset:10752
	v_mfma_f32_32x32x16_bf16 v[0:15], v[116:119], v[132:135], v[0:15]
	v_exp_f32_e32 v16, v16
	v_cvt_pk_bf16_f32 v253, v78, v79
	v_exp_f32_e32 v17, v17
	ds_read_b64_tr_b16 v[164:165], v183 offset:9280
	ds_read_b64_tr_b16 v[166:167], v183 offset:10816
	v_mfma_f32_32x32x16_bf16 v[0:15], v[120:123], v[136:139], v[0:15]
	v_exp_f32_e32 v18, v18
	v_cvt_pk_bf16_f32 v238, v16, v17
	v_exp_f32_e32 v19, v19
	ds_read_b64_tr_b16 v[190:191], v183 offset:12288
	ds_read_b64_tr_b16 v[192:193], v183 offset:13824
	v_mfma_f32_32x32x16_bf16 v[0:15], v[124:127], v[140:143], v[0:15]
	v_exp_f32_e32 v20, v20
	v_cvt_pk_bf16_f32 v239, v18, v19
	v_exp_f32_e32 v21, v21
	ds_read_b64_tr_b16 v[194:195], v183 offset:12352
	ds_read_b64_tr_b16 v[196:197], v183 offset:13888
	s_waitcnt lgkmcnt(8)
	v_mfma_f32_32x32x16_bf16 v[32:47], v[198:201], v[246:249], v[32:47]
	v_exp_f32_e32 v22, v22
	v_cvt_pk_bf16_f32 v240, v20, v21
	v_exp_f32_e32 v23, v23
	s_waitcnt vmcnt(0)
	ds_write_b128 v187, v[152:155] offset:21504
	v_mfma_f32_32x32x16_bf16 v[48:63], v[202:205], v[246:249], v[48:63]
	v_mfma_f32_16x16x32_bf16 v[174:177], v[178:181], v[246:249], v[174:177]
	v_exp_f32_e32 v24, v24
	v_cvt_pk_bf16_f32 v241, v22, v23
	v_exp_f32_e32 v25, v25
	ds_write_b128 v189, v[156:159] offset:30720
	v_mfma_f32_32x32x16_bf16 v[32:47], v[206:209], v[250:253], v[32:47]
	v_exp_f32_e32 v26, v26
	v_cvt_pk_bf16_f32 v242, v24, v25
	v_exp_f32_e32 v27, v27
	v_mfma_f32_32x32x16_bf16 v[48:63], v[234:237], v[250:253], v[48:63]
	v_mfma_f32_16x16x32_bf16 v[174:177], v[178:181], v[250:253], v[174:177]
	v_exp_f32_e32 v28, v28
	v_cvt_pk_bf16_f32 v243, v26, v27
	v_exp_f32_e32 v29, v29
	s_waitcnt lgkmcnt(0)
	s_barrier
	v_mfma_f32_32x32x16_bf16 v[32:47], v[160:163], v[238:241], v[32:47]
	ds_read_b128 v[96:99], v173 offset:21504
	ds_read_b128 v[100:103], v173 offset:21536
	v_exp_f32_e32 v30, v30
	v_cvt_pk_bf16_f32 v244, v28, v29
	v_exp_f32_e32 v31, v31
	v_mfma_f32_32x32x16_bf16 v[48:63], v[164:167], v[238:241], v[48:63]
	v_mfma_f32_16x16x32_bf16 v[174:177], v[178:181], v[238:241], v[174:177]
	ds_read_b128 v[104:107], v173 offset:21568
	ds_read_b128 v[108:111], v173 offset:21600
	v_exp_f32_e32 v0, v0
	v_cvt_pk_bf16_f32 v245, v30, v31
	v_exp_f32_e32 v1, v1
	s_nop 0
	v_mfma_f32_32x32x16_bf16 v[32:47], v[190:193], v[242:245], v[32:47]
	ds_read_b128 v[112:115], v173 offset:26112
	ds_read_b128 v[116:119], v173 offset:26144
	v_exp_f32_e32 v2, v2
	v_cvt_pk_bf16_f32 v246, v0, v1
	v_exp_f32_e32 v3, v3
	v_mfma_f32_32x32x16_bf16 v[48:63], v[194:197], v[242:245], v[48:63]
	v_mfma_f32_16x16x32_bf16 v[174:177], v[178:181], v[242:245], v[174:177]
	ds_read_b128 v[120:123], v173 offset:26176
	ds_read_b128 v[124:127], v173 offset:26208
	v_exp_f32_e32 v4, v4
	v_cvt_pk_bf16_f32 v247, v2, v3
	v_exp_f32_e32 v5, v5
	s_waitcnt lgkmcnt(4)
	v_mfma_f32_32x32x16_bf16 v[80:95], v[96:99], v[128:131], 0
	v_exp_f32_e32 v6, v6
	v_cvt_pk_bf16_f32 v248, v4, v5
	v_exp_f32_e32 v7, v7
	ds_read_b64_tr_b16 v[198:199], v183 offset:15360
	ds_read_b64_tr_b16 v[200:201], v183 offset:16896
	v_mfma_f32_32x32x16_bf16 v[80:95], v[100:103], v[132:135], v[80:95]
	v_exp_f32_e32 v8, v8
	v_cvt_pk_bf16_f32 v249, v6, v7
	v_exp_f32_e32 v9, v9
	ds_read_b64_tr_b16 v[202:203], v183 offset:15424
	ds_read_b64_tr_b16 v[204:205], v183 offset:16960
	v_mfma_f32_32x32x16_bf16 v[80:95], v[104:107], v[136:139], v[80:95]
	v_exp_f32_e32 v10, v10
	v_cvt_pk_bf16_f32 v250, v8, v9
	v_exp_f32_e32 v11, v11
	ds_read_b64_tr_b16 v[206:207], v183 offset:18432
	ds_read_b64_tr_b16 v[208:209], v183 offset:19968
	v_mfma_f32_32x32x16_bf16 v[80:95], v[108:111], v[140:143], v[80:95]
	v_exp_f32_e32 v12, v12
	v_cvt_pk_bf16_f32 v251, v10, v11
	v_exp_f32_e32 v13, v13
	ds_read_b64_tr_b16 v[234:235], v183 offset:18496
	ds_read_b64_tr_b16 v[236:237], v183 offset:20032
	s_waitcnt lgkmcnt(8)
	v_mfma_f32_32x32x16_bf16 v[64:79], v[112:115], v[128:131], 0
	v_exp_f32_e32 v14, v14
	v_cvt_pk_bf16_f32 v252, v12, v13
	v_exp_f32_e32 v15, v15
	ds_read_b64_tr_b16 v[160:161], v183 offset:30720
	ds_read_b64_tr_b16 v[162:163], v183 offset:32256
	v_mfma_f32_32x32x16_bf16 v[64:79], v[116:119], v[132:135], v[64:79]
	v_exp_f32_e32 v80, v80
	v_cvt_pk_bf16_f32 v253, v14, v15
	v_exp_f32_e32 v81, v81
	ds_read_b64_tr_b16 v[164:165], v183 offset:30784
	ds_read_b64_tr_b16 v[166:167], v183 offset:32320
	v_mfma_f32_32x32x16_bf16 v[64:79], v[120:123], v[136:139], v[64:79]
	v_exp_f32_e32 v82, v82
	v_cvt_pk_bf16_f32 v238, v80, v81
	v_exp_f32_e32 v83, v83
	ds_read_b64_tr_b16 v[190:191], v183 offset:33792
	ds_read_b64_tr_b16 v[192:193], v183 offset:35328
	v_mfma_f32_32x32x16_bf16 v[64:79], v[124:127], v[140:143], v[64:79]
	v_exp_f32_e32 v84, v84
	v_cvt_pk_bf16_f32 v239, v82, v83
	v_exp_f32_e32 v85, v85
	ds_read_b64_tr_b16 v[194:195], v183 offset:33856
	ds_read_b64_tr_b16 v[196:197], v183 offset:35392
	s_waitcnt lgkmcnt(8)
	v_mfma_f32_32x32x16_bf16 v[32:47], v[198:201], v[246:249], v[32:47]
	v_exp_f32_e32 v86, v86
	v_cvt_pk_bf16_f32 v240, v84, v85
	v_exp_f32_e32 v87, v87
	v_mfma_f32_32x32x16_bf16 v[48:63], v[202:205], v[246:249], v[48:63]
	v_mfma_f32_16x16x32_bf16 v[174:177], v[178:181], v[246:249], v[174:177]
	v_exp_f32_e32 v88, v88
	v_cvt_pk_bf16_f32 v241, v86, v87
	v_exp_f32_e32 v89, v89
	v_mfma_f32_32x32x16_bf16 v[32:47], v[206:209], v[250:253], v[32:47]
	v_exp_f32_e32 v90, v90
	v_cvt_pk_bf16_f32 v242, v88, v89
	v_exp_f32_e32 v91, v91
	v_mfma_f32_32x32x16_bf16 v[48:63], v[234:237], v[250:253], v[48:63]
	v_mfma_f32_16x16x32_bf16 v[174:177], v[178:181], v[250:253], v[174:177]
	v_exp_f32_e32 v92, v92
	v_cvt_pk_bf16_f32 v243, v90, v91
	v_exp_f32_e32 v93, v93
	s_waitcnt lgkmcnt(0)
	s_barrier
; __device__ __forceinline__ unsigned cvtpk(float lo, float hi) { f32x2_t v = {lo, hi}; bf16x2_t b = __builtin_convertvector(v, bf16x2_t); return __builtin_bit_cast(unsigned, b); }
; __device__ __forceinline__ float bflo(unsigned u) { return __uint_as_float(u << 16); }
; __device__ __forceinline__ float bfhi(unsigned u) { return __uint_as_float(u & 0xffff0000u); }
; __device__ __forceinline__ void attnB_unit(LAS unsigned char* lds, const Args& A, int unit, const float* kng, bool do_store = true) {
;     ...
;     const float inv = 1.0f / l;
;     bf16* yrow = (bf16*)(A.ws + WS_SBZ) + ((size_t)(b * 8192 + qblk * 256 + wave * 32 + ql) * 512 + hq * 64 + 4 * hh);
;     u32x2 zz[8];
; #pragma unroll
;     for (int g4 = 0; g4 < 4; ++g4) { zz[g4] = *(const u32x2*)(yrow + 8 * g4); zz[4 + g4] = *(const u32x2*)(yrow + 32 + 8 * g4); }
;     if (do_store)
; #pragma unroll
;     for (int g4 = 0; g4 < 4; ++g4) {
;         { bf16* p = yrow + 8 * g4; const u32x2 z = zz[g4];
;           u32x2 w; w.x = cvtpk(o0[4 * g4] * inv * bflo(z.x), o0[4 * g4 + 1] * inv * bfhi(z.x)); w.y = cvtpk(o0[4 * g4 + 2] * inv * bflo(z.y), o0[4 * g4 + 3] * inv * bfhi(z.y)); *(u32x2*)p = w; }
;         { bf16* p = yrow + 32 + 8 * g4; const u32x2 z = zz[4 + g4];
;           u32x2 w; w.x = cvtpk(o1[4 * g4] * inv * bflo(z.x), o1[4 * g4 + 1] * inv * bfhi(z.x)); w.y = cvtpk(o1[4 * g4 + 2] * inv * bflo(z.y), o1[4 * g4 + 3] * inv * bfhi(z.y)); *(u32x2*)p = w; }
	v_mfma_f32_32x32x16_bf16 v[32:47], v[160:163], v[238:241], v[32:47]
	s_lshl_b32 s4, s9, 13
	s_or_b32 s4, s4, s10
	s_lshl_b32 s60, s8, 7
	v_lshlrev_b32_e32 v184, 1, v227
	v_or_b32_e32 v0, s4, v210
	v_add_u32_e32 v0, v0, v211
	v_ashrrev_i32_e32 v1, 31, v0
	v_readlane_b32 s4, v254, 55
	v_lshlrev_b64 v[0:1], 10, v[0:1]
	v_readlane_b32 s5, v254, 56
	s_nop 1
	v_lshl_add_u64 v[0:1], s[4:5], 0, v[0:1]
	v_lshl_add_u64 v[0:1], v[0:1], 0, s[60:61]
	v_lshl_add_u64 v[0:1], v[0:1], 0, v[184:185]
	global_load_dwordx2 v[14:15], v[0:1], off
	global_load_dwordx2 v[16:17], v[0:1], off offset:64
	global_load_dwordx2 v[18:19], v[0:1], off offset:16
	global_load_dwordx2 v[12:13], v[0:1], off offset:80
	global_load_dwordx2 v[10:11], v[0:1], off offset:32
	global_load_dwordx2 v[6:7], v[0:1], off offset:96
	global_load_dwordx2 v[4:5], v[0:1], off offset:48
	global_load_dwordx2 v[2:3], v[0:1], off offset:112
	v_exp_f32_e32 v94, v94
	v_cvt_pk_bf16_f32 v244, v92, v93
	v_exp_f32_e32 v95, v95
	v_mfma_f32_32x32x16_bf16 v[48:63], v[164:167], v[238:241], v[48:63]
	v_mfma_f32_16x16x32_bf16 v[174:177], v[178:181], v[238:241], v[174:177]
	v_exp_f32_e32 v64, v64
	v_cvt_pk_bf16_f32 v245, v94, v95
	v_exp_f32_e32 v65, v65
	s_nop 0
	v_mfma_f32_32x32x16_bf16 v[32:47], v[190:193], v[242:245], v[32:47]
	v_exp_f32_e32 v66, v66
	v_cvt_pk_bf16_f32 v246, v64, v65
	v_exp_f32_e32 v67, v67
	v_mfma_f32_32x32x16_bf16 v[48:63], v[194:197], v[242:245], v[48:63]
	v_mfma_f32_16x16x32_bf16 v[174:177], v[178:181], v[242:245], v[174:177]
	v_exp_f32_e32 v68, v68
	v_cvt_pk_bf16_f32 v247, v66, v67
	v_exp_f32_e32 v69, v69
	v_exp_f32_e32 v70, v70
	v_cvt_pk_bf16_f32 v248, v68, v69
	v_exp_f32_e32 v71, v71
	ds_read_b64_tr_b16 v[198:199], v183 offset:36864
	ds_read_b64_tr_b16 v[200:201], v183 offset:38400
	v_exp_f32_e32 v72, v72
	v_cvt_pk_bf16_f32 v249, v70, v71
	v_exp_f32_e32 v73, v73
	ds_read_b64_tr_b16 v[202:203], v183 offset:36928
	ds_read_b64_tr_b16 v[204:205], v183 offset:38464
	v_exp_f32_e32 v74, v74
	v_cvt_pk_bf16_f32 v250, v72, v73
	v_exp_f32_e32 v75, v75
	ds_read_b64_tr_b16 v[206:207], v183 offset:39936
	ds_read_b64_tr_b16 v[208:209], v183 offset:41472
	v_exp_f32_e32 v76, v76
	v_cvt_pk_bf16_f32 v251, v74, v75
	v_exp_f32_e32 v77, v77
	ds_read_b64_tr_b16 v[234:235], v183 offset:40000
	ds_read_b64_tr_b16 v[236:237], v183 offset:41536
	v_exp_f32_e32 v78, v78
	v_cvt_pk_bf16_f32 v252, v76, v77
	v_exp_f32_e32 v79, v79
	s_nop 0
	v_cvt_pk_bf16_f32 v253, v78, v79
	s_waitcnt lgkmcnt(0)
	v_mfma_f32_32x32x16_bf16 v[32:47], v[198:201], v[246:249], v[32:47]
	v_mfma_f32_32x32x16_bf16 v[48:63], v[202:205], v[246:249], v[48:63]
	v_mfma_f32_16x16x32_bf16 v[174:177], v[178:181], v[246:249], v[174:177]
	v_mfma_f32_32x32x16_bf16 v[32:47], v[206:209], v[250:253], v[32:47]
	v_mfma_f32_32x32x16_bf16 v[48:63], v[234:237], v[250:253], v[48:63]
	v_mfma_f32_16x16x32_bf16 v[174:177], v[178:181], v[250:253], v[174:177]
	s_nop 7
	v_and_b32_e32 v214, 15, v217
	v_lshlrev_b32_e32 v214, 2, v214
	v_and_b32_e32 v219, 16, v217
	ds_bpermute_b32 v215, v214, v174
	ds_bpermute_b32 v218, v214, v175
	v_cmp_ne_u32_e32 vcc, 0, v219
	s_waitcnt lgkmcnt(0)
	s_nop 1
	v_cndmask_b32_e32 v8, v215, v218, vcc
	v_div_scale_f32 v9, s[4:5], v8, v8, 1.0
	v_rcp_f32_e32 v20, v9
	s_nop 0
	v_fma_f32 v21, -v9, v20, 1.0
	v_fmac_f32_e32 v20, v21, v20
	v_div_scale_f32 v21, vcc, 1.0, v8, 1.0
	v_mul_f32_e32 v22, v21, v20
	v_fma_f32 v23, -v9, v22, v21
	v_fmac_f32_e32 v22, v23, v20
	v_fma_f32 v9, -v9, v22, v21
	v_div_fmas_f32 v9, v9, v20, v22
	v_div_fixup_f32 v8, v9, v8, 1.0
	v_pk_mul_f32 v[20:21], v[32:33], v[8:9] op_sel_hi:[1,0]
	s_waitcnt vmcnt(7)
; __device__ __forceinline__ unsigned cvtpk(float lo, float hi) { f32x2_t v = {lo, hi}; bf16x2_t b = __builtin_convertvector(v, bf16x2_t); return __builtin_bit_cast(unsigned, b); }
; __device__ __forceinline__ float bflo(unsigned u) { return __uint_as_float(u << 16); }
; __device__ __forceinline__ float bfhi(unsigned u) { return __uint_as_float(u & 0xffff0000u); }
; __device__ __forceinline__ void attnB_unit(LAS unsigned char* lds, const Args& A, int unit, const float* kng, bool do_store = true) {
;     ...
;     const float inv = 1.0f / l;
;     bf16* yrow = (bf16*)(A.ws + WS_SBZ) + ((size_t)(b * 8192 + qblk * 256 + wave * 32 + ql) * 512 + hq * 64 + 4 * hh);
;     u32x2 zz[8];
; #pragma unroll
;     for (int g4 = 0; g4 < 4; ++g4) { zz[g4] = *(const u32x2*)(yrow + 8 * g4); zz[4 + g4] = *(const u32x2*)(yrow + 32 + 8 * g4); }
;     if (do_store)
; #pragma unroll
;     for (int g4 = 0; g4 < 4; ++g4) {
;         { bf16* p = yrow + 8 * g4; const u32x2 z = zz[g4];
;           u32x2 w; w.x = cvtpk(o0[4 * g4] * inv * bflo(z.x), o0[4 * g4 + 1] * inv * bfhi(z.x)); w.y = cvtpk(o0[4 * g4 + 2] * inv * bflo(z.y), o0[4 * g4 + 3] * inv * bfhi(z.y)); *(u32x2*)p = w; }
;         { bf16* p = yrow + 32 + 8 * g4; const u32x2 z = zz[4 + g4];
;           u32x2 w; w.x = cvtpk(o1[4 * g4] * inv * bflo(z.x), o1[4 * g4 + 1] * inv * bfhi(z.x)); w.y = cvtpk(o1[4 * g4 + 2] * inv * bflo(z.y), o1[4 * g4 + 3] * inv * bfhi(z.y)); *(u32x2*)p = w; }
;     }
	v_lshlrev_b32_e32 v22, 16, v14
	v_and_b32_e32 v23, 0xffff0000, v14
	v_pk_mul_f32 v[20:21], v[20:21], v[22:23]
	v_lshlrev_b32_e32 v22, 16, v15
	v_cvt_pk_bf16_f32 v14, v20, v21
	v_pk_mul_f32 v[20:21], v[34:35], v[8:9] op_sel_hi:[1,0]
	v_and_b32_e32 v23, 0xffff0000, v15
	v_pk_mul_f32 v[20:21], v[20:21], v[22:23]
	s_nop 0
	v_cvt_pk_bf16_f32 v15, v20, v21
	global_store_dwordx2 v[0:1], v[14:15], off
	v_pk_mul_f32 v[14:15], v[48:49], v[8:9] op_sel_hi:[1,0]
	s_waitcnt vmcnt(7)
	v_lshlrev_b32_e32 v20, 16, v16
	v_and_b32_e32 v21, 0xffff0000, v16
	v_pk_mul_f32 v[14:15], v[14:15], v[20:21]
	v_pk_mul_f32 v[20:21], v[50:51], v[8:9] op_sel_hi:[1,0]
	v_lshlrev_b32_e32 v16, 16, v17
	v_and_b32_e32 v17, 0xffff0000, v17
	v_pk_mul_f32 v[16:17], v[20:21], v[16:17]
	v_cvt_pk_bf16_f32 v14, v14, v15
	v_cvt_pk_bf16_f32 v15, v16, v17
	global_store_dwordx2 v[0:1], v[14:15], off offset:64
	v_pk_mul_f32 v[14:15], v[36:37], v[8:9] op_sel_hi:[1,0]
	s_waitcnt vmcnt(7)
	v_lshlrev_b32_e32 v16, 16, v18
	v_and_b32_e32 v17, 0xffff0000, v18
	v_pk_mul_f32 v[14:15], v[14:15], v[16:17]
	v_pk_mul_f32 v[16:17], v[38:39], v[8:9] op_sel_hi:[1,0]
	v_lshlrev_b32_e32 v18, 16, v19
	v_and_b32_e32 v19, 0xffff0000, v19
	v_pk_mul_f32 v[16:17], v[16:17], v[18:19]
	v_cvt_pk_bf16_f32 v14, v14, v15
	v_cvt_pk_bf16_f32 v15, v16, v17
	global_store_dwordx2 v[0:1], v[14:15], off offset:16
	v_pk_mul_f32 v[14:15], v[52:53], v[8:9] op_sel_hi:[1,0]
	s_waitcnt vmcnt(7)
	v_lshlrev_b32_e32 v16, 16, v12
	v_and_b32_e32 v17, 0xffff0000, v12
	v_pk_mul_f32 v[14:15], v[14:15], v[16:17]
	v_lshlrev_b32_e32 v16, 16, v13
	v_cvt_pk_bf16_f32 v12, v14, v15
	v_pk_mul_f32 v[14:15], v[54:55], v[8:9] op_sel_hi:[1,0]
	v_and_b32_e32 v17, 0xffff0000, v13
	v_pk_mul_f32 v[14:15], v[14:15], v[16:17]
	s_nop 0
	v_cvt_pk_bf16_f32 v13, v14, v15
	global_store_dwordx2 v[0:1], v[12:13], off offset:80
	v_pk_mul_f32 v[12:13], v[40:41], v[8:9] op_sel_hi:[1,0]
	s_waitcnt vmcnt(7)
	v_lshlrev_b32_e32 v14, 16, v10
	v_and_b32_e32 v15, 0xffff0000, v10
	v_pk_mul_f32 v[12:13], v[12:13], v[14:15]
	v_lshlrev_b32_e32 v14, 16, v11
	v_cvt_pk_bf16_f32 v10, v12, v13
	v_pk_mul_f32 v[12:13], v[42:43], v[8:9] op_sel_hi:[1,0]
	v_and_b32_e32 v15, 0xffff0000, v11
	v_pk_mul_f32 v[12:13], v[12:13], v[14:15]
	s_nop 0
	v_cvt_pk_bf16_f32 v11, v12, v13
	global_store_dwordx2 v[0:1], v[10:11], off offset:32
	v_pk_mul_f32 v[10:11], v[56:57], v[8:9] op_sel_hi:[1,0]
	s_waitcnt vmcnt(7)
	v_lshlrev_b32_e32 v12, 16, v6
	v_and_b32_e32 v13, 0xffff0000, v6
	v_pk_mul_f32 v[10:11], v[10:11], v[12:13]
	v_lshlrev_b32_e32 v12, 16, v7
	v_cvt_pk_bf16_f32 v6, v10, v11
	v_pk_mul_f32 v[10:11], v[58:59], v[8:9] op_sel_hi:[1,0]
	v_and_b32_e32 v13, 0xffff0000, v7
	v_pk_mul_f32 v[10:11], v[10:11], v[12:13]
	s_nop 0
	v_cvt_pk_bf16_f32 v7, v10, v11
	global_store_dwordx2 v[0:1], v[6:7], off offset:96
	v_pk_mul_f32 v[6:7], v[44:45], v[8:9] op_sel_hi:[1,0]
	s_waitcnt vmcnt(7)
	v_lshlrev_b32_e32 v10, 16, v4
	v_and_b32_e32 v11, 0xffff0000, v4
	v_pk_mul_f32 v[6:7], v[6:7], v[10:11]
	v_lshlrev_b32_e32 v10, 16, v5
	v_cvt_pk_bf16_f32 v4, v6, v7
	v_pk_mul_f32 v[6:7], v[46:47], v[8:9] op_sel_hi:[1,0]
	v_and_b32_e32 v11, 0xffff0000, v5
	v_pk_mul_f32 v[6:7], v[6:7], v[10:11]
	s_nop 0
	v_cvt_pk_bf16_f32 v5, v6, v7
	global_store_dwordx2 v[0:1], v[4:5], off offset:48
	v_pk_mul_f32 v[4:5], v[60:61], v[8:9] op_sel_hi:[1,0]
	s_waitcnt vmcnt(7)
	v_lshlrev_b32_e32 v6, 16, v2
	v_and_b32_e32 v7, 0xffff0000, v2
	v_pk_mul_f32 v[4:5], v[4:5], v[6:7]
	v_lshlrev_b32_e32 v6, 16, v3
	v_cvt_pk_bf16_f32 v2, v4, v5
	v_pk_mul_f32 v[4:5], v[62:63], v[8:9] op_sel_hi:[1,0]
	v_and_b32_e32 v7, 0xffff0000, v3
	v_pk_mul_f32 v[4:5], v[4:5], v[6:7]
	s_nop 0
	v_cvt_pk_bf16_f32 v3, v4, v5
	global_store_dwordx2 v[0:1], v[2:3], off offset:112
	s_branch .LBB0_276
	v_mov_b32_e32 v233, 0
	s_branch .LBB0_275
